# speedup vs baseline: 1.0030x; 1.0030x over previous
; __device__ __forceinline__ unsigned pack2(float a, float b) { return (unsigned)f2bf(a) | ((unsigned)f2bf(b) << 16); }
; __device__ __forceinline__ float bflo(unsigned u) { return __uint_as_float(u << 16); }
; __device__ __forceinline__ float bfhi(unsigned u) { return __uint_as_float(u & 0xffff0000u); }
; __device__ void phase_retscan(const Params& p) {
;     ...
;     for (int n0 = 0; n0 < 128; n0 += 16) {
;       unsigned v[16];
; #pragma unroll
;       for (int j = 0; j < 16; ++j) v[j] = ptr[(long)(n0 + j) * 4 * 16384];
; #pragma unroll
;       for (int j = 0; j < 16; ++j) {
;         ptr[(long)(n0 + j) * 4 * 16384] = pack2(st0, st1);
;         st0 = cd * st0 + bflo(v[j]); st1 = cd * st1 + bfhi(v[j]);
;       }
;     }
.LBB0_954:
	s_mov_b64 s[38:39], 0x40000
	v_mov_b64_e32 v[10:11], v[6:7]
	global_load_dword v144, v[10:11], off
	v_lshl_add_u64 v[10:11], v[10:11], 0, s[38:39]
	global_load_dword v145, v[10:11], off
	v_lshl_add_u64 v[10:11], v[10:11], 0, s[38:39]
	global_load_dword v146, v[10:11], off
	v_lshl_add_u64 v[10:11], v[10:11], 0, s[38:39]
	global_load_dword v147, v[10:11], off
	v_lshl_add_u64 v[10:11], v[10:11], 0, s[38:39]
	global_load_dword v148, v[10:11], off
	v_lshl_add_u64 v[10:11], v[10:11], 0, s[38:39]
	global_load_dword v149, v[10:11], off
	v_lshl_add_u64 v[10:11], v[10:11], 0, s[38:39]
	global_load_dword v150, v[10:11], off
	v_lshl_add_u64 v[10:11], v[10:11], 0, s[38:39]
	global_load_dword v151, v[10:11], off
	v_lshl_add_u64 v[10:11], v[10:11], 0, s[38:39]
	global_load_dword v152, v[10:11], off
	v_lshl_add_u64 v[10:11], v[10:11], 0, s[38:39]
	global_load_dword v153, v[10:11], off
	v_lshl_add_u64 v[10:11], v[10:11], 0, s[38:39]
	global_load_dword v154, v[10:11], off
	v_lshl_add_u64 v[10:11], v[10:11], 0, s[38:39]
	global_load_dword v155, v[10:11], off
	v_lshl_add_u64 v[10:11], v[10:11], 0, s[38:39]
	global_load_dword v156, v[10:11], off
	v_lshl_add_u64 v[10:11], v[10:11], 0, s[38:39]
	global_load_dword v157, v[10:11], off
	v_lshl_add_u64 v[10:11], v[10:11], 0, s[38:39]
	global_load_dword v158, v[10:11], off
	v_lshl_add_u64 v[10:11], v[10:11], 0, s[38:39]
	global_load_dword v159, v[10:11], off
	v_lshl_add_u64 v[10:11], v[10:11], 0, s[38:39]
	global_load_dword v160, v[10:11], off
	v_lshl_add_u64 v[10:11], v[10:11], 0, s[38:39]
	global_load_dword v161, v[10:11], off
	v_lshl_add_u64 v[10:11], v[10:11], 0, s[38:39]
	global_load_dword v162, v[10:11], off
	v_lshl_add_u64 v[10:11], v[10:11], 0, s[38:39]
	global_load_dword v163, v[10:11], off
	v_lshl_add_u64 v[10:11], v[10:11], 0, s[38:39]
	global_load_dword v164, v[10:11], off
	v_lshl_add_u64 v[10:11], v[10:11], 0, s[38:39]
	global_load_dword v165, v[10:11], off
	v_lshl_add_u64 v[10:11], v[10:11], 0, s[38:39]
	global_load_dword v166, v[10:11], off
	v_lshl_add_u64 v[10:11], v[10:11], 0, s[38:39]
	global_load_dword v167, v[10:11], off
	v_lshl_add_u64 v[10:11], v[10:11], 0, s[38:39]
	global_load_dword v168, v[10:11], off
	v_lshl_add_u64 v[10:11], v[10:11], 0, s[38:39]
	global_load_dword v169, v[10:11], off
	v_lshl_add_u64 v[10:11], v[10:11], 0, s[38:39]
	global_load_dword v170, v[10:11], off
	v_lshl_add_u64 v[10:11], v[10:11], 0, s[38:39]
	global_load_dword v171, v[10:11], off
	v_lshl_add_u64 v[10:11], v[10:11], 0, s[38:39]
	global_load_dword v172, v[10:11], off
	v_lshl_add_u64 v[10:11], v[10:11], 0, s[38:39]
	global_load_dword v173, v[10:11], off
	v_lshl_add_u64 v[10:11], v[10:11], 0, s[38:39]
	global_load_dword v174, v[10:11], off
	v_lshl_add_u64 v[10:11], v[10:11], 0, s[38:39]
	global_load_dword v175, v[10:11], off
	s_add_i32 s11, s11, 32
	s_waitcnt vmcnt(31)
	v_bfe_u32 v12, v9, 16, 1
	v_bfe_u32 v13, v8, 16, 1
	v_add3_u32 v12, v9, v12, s65
	v_add3_u32 v13, v8, v13, s65
	v_lshrrev_b32_e32 v12, 16, v12
	v_and_b32_e32 v14, 0xffff0000, v144
	v_lshlrev_b32_e32 v15, 16, v144
	v_and_or_b32 v12, v13, s14, v12
	v_pk_fma_f32 v[8:9], v[4:5], v[8:9], v[14:15]
	global_store_dword v[6:7], v12, off
	v_lshl_add_u64 v[6:7], v[6:7], 0, s[38:39]
	s_waitcnt vmcnt(31)
	v_bfe_u32 v12, v9, 16, 1
	v_bfe_u32 v13, v8, 16, 1
	v_add3_u32 v12, v9, v12, s65
	v_add3_u32 v13, v8, v13, s65
	v_lshrrev_b32_e32 v12, 16, v12
	v_and_b32_e32 v14, 0xffff0000, v145
	v_lshlrev_b32_e32 v15, 16, v145
	v_and_or_b32 v12, v13, s14, v12
	v_pk_fma_f32 v[8:9], v[4:5], v[8:9], v[14:15]
	global_store_dword v[6:7], v12, off
	v_lshl_add_u64 v[6:7], v[6:7], 0, s[38:39]
	s_waitcnt vmcnt(31)
	v_bfe_u32 v12, v9, 16, 1
	v_bfe_u32 v13, v8, 16, 1
	v_add3_u32 v12, v9, v12, s65
	v_add3_u32 v13, v8, v13, s65
	v_lshrrev_b32_e32 v12, 16, v12
	v_and_b32_e32 v14, 0xffff0000, v146
	v_lshlrev_b32_e32 v15, 16, v146
	v_and_or_b32 v12, v13, s14, v12
	v_pk_fma_f32 v[8:9], v[4:5], v[8:9], v[14:15]
	global_store_dword v[6:7], v12, off
	v_lshl_add_u64 v[6:7], v[6:7], 0, s[38:39]
	s_waitcnt vmcnt(31)
	v_bfe_u32 v12, v9, 16, 1
	v_bfe_u32 v13, v8, 16, 1
	v_add3_u32 v12, v9, v12, s65
	v_add3_u32 v13, v8, v13, s65
	v_lshrrev_b32_e32 v12, 16, v12
	v_and_b32_e32 v14, 0xffff0000, v147
	v_lshlrev_b32_e32 v15, 16, v147
	v_and_or_b32 v12, v13, s14, v12
	v_pk_fma_f32 v[8:9], v[4:5], v[8:9], v[14:15]
	global_store_dword v[6:7], v12, off
	v_lshl_add_u64 v[6:7], v[6:7], 0, s[38:39]
	s_waitcnt vmcnt(31)
	v_bfe_u32 v12, v9, 16, 1
	v_bfe_u32 v13, v8, 16, 1
	v_add3_u32 v12, v9, v12, s65
	v_add3_u32 v13, v8, v13, s65
	v_lshrrev_b32_e32 v12, 16, v12
	v_and_b32_e32 v14, 0xffff0000, v148
	v_lshlrev_b32_e32 v15, 16, v148
	v_and_or_b32 v12, v13, s14, v12
	v_pk_fma_f32 v[8:9], v[4:5], v[8:9], v[14:15]
	global_store_dword v[6:7], v12, off
	v_lshl_add_u64 v[6:7], v[6:7], 0, s[38:39]
	s_waitcnt vmcnt(31)
	v_bfe_u32 v12, v9, 16, 1
	v_bfe_u32 v13, v8, 16, 1
	v_add3_u32 v12, v9, v12, s65
	v_add3_u32 v13, v8, v13, s65
	v_lshrrev_b32_e32 v12, 16, v12
	v_and_b32_e32 v14, 0xffff0000, v149
	v_lshlrev_b32_e32 v15, 16, v149
	v_and_or_b32 v12, v13, s14, v12
	v_pk_fma_f32 v[8:9], v[4:5], v[8:9], v[14:15]
	global_store_dword v[6:7], v12, off
	v_lshl_add_u64 v[6:7], v[6:7], 0, s[38:39]
	s_waitcnt vmcnt(31)
	v_bfe_u32 v12, v9, 16, 1
	v_bfe_u32 v13, v8, 16, 1
	v_add3_u32 v12, v9, v12, s65
	v_add3_u32 v13, v8, v13, s65
	v_lshrrev_b32_e32 v12, 16, v12
	v_and_b32_e32 v14, 0xffff0000, v150
	v_lshlrev_b32_e32 v15, 16, v150
	v_and_or_b32 v12, v13, s14, v12
	v_pk_fma_f32 v[8:9], v[4:5], v[8:9], v[14:15]
	global_store_dword v[6:7], v12, off
	v_lshl_add_u64 v[6:7], v[6:7], 0, s[38:39]
	s_waitcnt vmcnt(31)
; __device__ __forceinline__ unsigned pack2(float a, float b) { return (unsigned)f2bf(a) | ((unsigned)f2bf(b) << 16); }
; __device__ __forceinline__ float bflo(unsigned u) { return __uint_as_float(u << 16); }
; __device__ __forceinline__ float bfhi(unsigned u) { return __uint_as_float(u & 0xffff0000u); }
; __device__ void phase_retscan(const Params& p) {
;     ...
; #pragma unroll
;       for (int j = 0; j < 16; ++j) {
;         ptr[(long)(n0 + j) * 4 * 16384] = pack2(st0, st1);
;         st0 = cd * st0 + bflo(v[j]); st1 = cd * st1 + bfhi(v[j]);
;       }
	v_bfe_u32 v12, v9, 16, 1
	v_bfe_u32 v13, v8, 16, 1
	v_add3_u32 v12, v9, v12, s65
	v_add3_u32 v13, v8, v13, s65
	v_lshrrev_b32_e32 v12, 16, v12
	v_and_b32_e32 v14, 0xffff0000, v151
	v_lshlrev_b32_e32 v15, 16, v151
	v_and_or_b32 v12, v13, s14, v12
	v_pk_fma_f32 v[8:9], v[4:5], v[8:9], v[14:15]
	global_store_dword v[6:7], v12, off
	v_lshl_add_u64 v[6:7], v[6:7], 0, s[38:39]
	s_waitcnt vmcnt(31)
	v_bfe_u32 v12, v9, 16, 1
	v_bfe_u32 v13, v8, 16, 1
	v_add3_u32 v12, v9, v12, s65
	v_add3_u32 v13, v8, v13, s65
	v_lshrrev_b32_e32 v12, 16, v12
	v_and_b32_e32 v14, 0xffff0000, v152
	v_lshlrev_b32_e32 v15, 16, v152
	v_and_or_b32 v12, v13, s14, v12
	v_pk_fma_f32 v[8:9], v[4:5], v[8:9], v[14:15]
	global_store_dword v[6:7], v12, off
	v_lshl_add_u64 v[6:7], v[6:7], 0, s[38:39]
	s_waitcnt vmcnt(31)
	v_bfe_u32 v12, v9, 16, 1
	v_bfe_u32 v13, v8, 16, 1
	v_add3_u32 v12, v9, v12, s65
	v_add3_u32 v13, v8, v13, s65
	v_lshrrev_b32_e32 v12, 16, v12
	v_and_b32_e32 v14, 0xffff0000, v153
	v_lshlrev_b32_e32 v15, 16, v153
	v_and_or_b32 v12, v13, s14, v12
	v_pk_fma_f32 v[8:9], v[4:5], v[8:9], v[14:15]
	global_store_dword v[6:7], v12, off
	v_lshl_add_u64 v[6:7], v[6:7], 0, s[38:39]
	s_waitcnt vmcnt(31)
	v_bfe_u32 v12, v9, 16, 1
	v_bfe_u32 v13, v8, 16, 1
	v_add3_u32 v12, v9, v12, s65
	v_add3_u32 v13, v8, v13, s65
	v_lshrrev_b32_e32 v12, 16, v12
	v_and_b32_e32 v14, 0xffff0000, v154
	v_lshlrev_b32_e32 v15, 16, v154
	v_and_or_b32 v12, v13, s14, v12
	v_pk_fma_f32 v[8:9], v[4:5], v[8:9], v[14:15]
	global_store_dword v[6:7], v12, off
	v_lshl_add_u64 v[6:7], v[6:7], 0, s[38:39]
	s_waitcnt vmcnt(31)
	v_bfe_u32 v12, v9, 16, 1
	v_bfe_u32 v13, v8, 16, 1
	v_add3_u32 v12, v9, v12, s65
	v_add3_u32 v13, v8, v13, s65
	v_lshrrev_b32_e32 v12, 16, v12
	v_and_b32_e32 v14, 0xffff0000, v155
	v_lshlrev_b32_e32 v15, 16, v155
	v_and_or_b32 v12, v13, s14, v12
	v_pk_fma_f32 v[8:9], v[4:5], v[8:9], v[14:15]
	global_store_dword v[6:7], v12, off
	v_lshl_add_u64 v[6:7], v[6:7], 0, s[38:39]
	s_waitcnt vmcnt(31)
	v_bfe_u32 v12, v9, 16, 1
	v_bfe_u32 v13, v8, 16, 1
	v_add3_u32 v12, v9, v12, s65
	v_add3_u32 v13, v8, v13, s65
	v_lshrrev_b32_e32 v12, 16, v12
	v_and_b32_e32 v14, 0xffff0000, v156
	v_lshlrev_b32_e32 v15, 16, v156
	v_and_or_b32 v12, v13, s14, v12
	v_pk_fma_f32 v[8:9], v[4:5], v[8:9], v[14:15]
	global_store_dword v[6:7], v12, off
	v_lshl_add_u64 v[6:7], v[6:7], 0, s[38:39]
	s_waitcnt vmcnt(31)
	v_bfe_u32 v12, v9, 16, 1
	v_bfe_u32 v13, v8, 16, 1
	v_add3_u32 v12, v9, v12, s65
	v_add3_u32 v13, v8, v13, s65
	v_lshrrev_b32_e32 v12, 16, v12
	v_and_b32_e32 v14, 0xffff0000, v157
	v_lshlrev_b32_e32 v15, 16, v157
	v_and_or_b32 v12, v13, s14, v12
	v_pk_fma_f32 v[8:9], v[4:5], v[8:9], v[14:15]
	global_store_dword v[6:7], v12, off
	v_lshl_add_u64 v[6:7], v[6:7], 0, s[38:39]
	s_waitcnt vmcnt(31)
	v_bfe_u32 v12, v9, 16, 1
	v_bfe_u32 v13, v8, 16, 1
	v_add3_u32 v12, v9, v12, s65
	v_add3_u32 v13, v8, v13, s65
	v_lshrrev_b32_e32 v12, 16, v12
	v_and_b32_e32 v14, 0xffff0000, v158
	v_lshlrev_b32_e32 v15, 16, v158
	v_and_or_b32 v12, v13, s14, v12
	v_pk_fma_f32 v[8:9], v[4:5], v[8:9], v[14:15]
	global_store_dword v[6:7], v12, off
	v_lshl_add_u64 v[6:7], v[6:7], 0, s[38:39]
	s_waitcnt vmcnt(31)
	v_bfe_u32 v12, v9, 16, 1
	v_bfe_u32 v13, v8, 16, 1
	v_add3_u32 v12, v9, v12, s65
	v_add3_u32 v13, v8, v13, s65
	v_lshrrev_b32_e32 v12, 16, v12
	v_and_b32_e32 v14, 0xffff0000, v159
	v_lshlrev_b32_e32 v15, 16, v159
	v_and_or_b32 v12, v13, s14, v12
	v_pk_fma_f32 v[8:9], v[4:5], v[8:9], v[14:15]
	global_store_dword v[6:7], v12, off
	v_lshl_add_u64 v[6:7], v[6:7], 0, s[38:39]
	s_waitcnt vmcnt(31)
	v_bfe_u32 v12, v9, 16, 1
	v_bfe_u32 v13, v8, 16, 1
	v_add3_u32 v12, v9, v12, s65
	v_add3_u32 v13, v8, v13, s65
	v_lshrrev_b32_e32 v12, 16, v12
	v_and_b32_e32 v14, 0xffff0000, v160
	v_lshlrev_b32_e32 v15, 16, v160
	v_and_or_b32 v12, v13, s14, v12
	v_pk_fma_f32 v[8:9], v[4:5], v[8:9], v[14:15]
	global_store_dword v[6:7], v12, off
	v_lshl_add_u64 v[6:7], v[6:7], 0, s[38:39]
	s_waitcnt vmcnt(31)
	v_bfe_u32 v12, v9, 16, 1
	v_bfe_u32 v13, v8, 16, 1
	v_add3_u32 v12, v9, v12, s65
	v_add3_u32 v13, v8, v13, s65
	v_lshrrev_b32_e32 v12, 16, v12
	v_and_b32_e32 v14, 0xffff0000, v161
	v_lshlrev_b32_e32 v15, 16, v161
	v_and_or_b32 v12, v13, s14, v12
	v_pk_fma_f32 v[8:9], v[4:5], v[8:9], v[14:15]
	global_store_dword v[6:7], v12, off
	v_lshl_add_u64 v[6:7], v[6:7], 0, s[38:39]
	s_waitcnt vmcnt(31)
	v_bfe_u32 v12, v9, 16, 1
	v_bfe_u32 v13, v8, 16, 1
	v_add3_u32 v12, v9, v12, s65
	v_add3_u32 v13, v8, v13, s65
	v_lshrrev_b32_e32 v12, 16, v12
	v_and_b32_e32 v14, 0xffff0000, v162
	v_lshlrev_b32_e32 v15, 16, v162
	v_and_or_b32 v12, v13, s14, v12
	v_pk_fma_f32 v[8:9], v[4:5], v[8:9], v[14:15]
	global_store_dword v[6:7], v12, off
	v_lshl_add_u64 v[6:7], v[6:7], 0, s[38:39]
	s_waitcnt vmcnt(31)
	v_bfe_u32 v12, v9, 16, 1
	v_bfe_u32 v13, v8, 16, 1
	v_add3_u32 v12, v9, v12, s65
	v_add3_u32 v13, v8, v13, s65
	v_lshrrev_b32_e32 v12, 16, v12
	v_and_b32_e32 v14, 0xffff0000, v163
	v_lshlrev_b32_e32 v15, 16, v163
	v_and_or_b32 v12, v13, s14, v12
	v_pk_fma_f32 v[8:9], v[4:5], v[8:9], v[14:15]
	global_store_dword v[6:7], v12, off
	v_lshl_add_u64 v[6:7], v[6:7], 0, s[38:39]
	s_waitcnt vmcnt(31)
; __device__ __forceinline__ int otid() { int t = threadIdx.x; asm volatile("" : "+v"(t)); return t; }
; __device__ __forceinline__ unsigned pack2(float a, float b) { return (unsigned)f2bf(a) | ((unsigned)f2bf(b) << 16); }
; __device__ __forceinline__ float bflo(unsigned u) { return __uint_as_float(u << 16); }
; __device__ __forceinline__ float bfhi(unsigned u) { return __uint_as_float(u & 0xffff0000u); }
; __device__ void phase_retscan(const Params& p) {
;     ...
;   for (long e2 = (long)blockIdx.x * NTHR + otid(); e2 < 4L * 16384; e2 += nthreads) {
;     int hh = (int)(e2 >> 13);
;     float cd = exp2f(log2_gamma(hh) * 128.f);
;     unsigned* ptr = (unsigned*)p.KV + e2;
;     float st0 = 0.f, st1 = 0.f;
;     for (int n0 = 0; n0 < 128; n0 += 16) {
;       unsigned v[16];
; #pragma unroll
;       for (int j = 0; j < 16; ++j) v[j] = ptr[(long)(n0 + j) * 4 * 16384];
; #pragma unroll
;       for (int j = 0; j < 16; ++j) {
;         ptr[(long)(n0 + j) * 4 * 16384] = pack2(st0, st1);
;         st0 = cd * st0 + bflo(v[j]); st1 = cd * st1 + bfhi(v[j]);
;       }
;     }
	v_bfe_u32 v12, v9, 16, 1
	v_bfe_u32 v13, v8, 16, 1
	v_add3_u32 v12, v9, v12, s65
	v_add3_u32 v13, v8, v13, s65
	v_lshrrev_b32_e32 v12, 16, v12
	v_and_b32_e32 v14, 0xffff0000, v164
	v_lshlrev_b32_e32 v15, 16, v164
	v_and_or_b32 v12, v13, s14, v12
	v_pk_fma_f32 v[8:9], v[4:5], v[8:9], v[14:15]
	global_store_dword v[6:7], v12, off
	v_lshl_add_u64 v[6:7], v[6:7], 0, s[38:39]
	s_waitcnt vmcnt(31)
	v_bfe_u32 v12, v9, 16, 1
	v_bfe_u32 v13, v8, 16, 1
	v_add3_u32 v12, v9, v12, s65
	v_add3_u32 v13, v8, v13, s65
	v_lshrrev_b32_e32 v12, 16, v12
	v_and_b32_e32 v14, 0xffff0000, v165
	v_lshlrev_b32_e32 v15, 16, v165
	v_and_or_b32 v12, v13, s14, v12
	v_pk_fma_f32 v[8:9], v[4:5], v[8:9], v[14:15]
	global_store_dword v[6:7], v12, off
	v_lshl_add_u64 v[6:7], v[6:7], 0, s[38:39]
	s_waitcnt vmcnt(31)
	v_bfe_u32 v12, v9, 16, 1
	v_bfe_u32 v13, v8, 16, 1
	v_add3_u32 v12, v9, v12, s65
	v_add3_u32 v13, v8, v13, s65
	v_lshrrev_b32_e32 v12, 16, v12
	v_and_b32_e32 v14, 0xffff0000, v166
	v_lshlrev_b32_e32 v15, 16, v166
	v_and_or_b32 v12, v13, s14, v12
	v_pk_fma_f32 v[8:9], v[4:5], v[8:9], v[14:15]
	global_store_dword v[6:7], v12, off
	v_lshl_add_u64 v[6:7], v[6:7], 0, s[38:39]
	s_waitcnt vmcnt(31)
	v_bfe_u32 v12, v9, 16, 1
	v_bfe_u32 v13, v8, 16, 1
	v_add3_u32 v12, v9, v12, s65
	v_add3_u32 v13, v8, v13, s65
	v_lshrrev_b32_e32 v12, 16, v12
	v_and_b32_e32 v14, 0xffff0000, v167
	v_lshlrev_b32_e32 v15, 16, v167
	v_and_or_b32 v12, v13, s14, v12
	v_pk_fma_f32 v[8:9], v[4:5], v[8:9], v[14:15]
	global_store_dword v[6:7], v12, off
	v_lshl_add_u64 v[6:7], v[6:7], 0, s[38:39]
	s_waitcnt vmcnt(31)
	v_bfe_u32 v12, v9, 16, 1
	v_bfe_u32 v13, v8, 16, 1
	v_add3_u32 v12, v9, v12, s65
	v_add3_u32 v13, v8, v13, s65
	v_lshrrev_b32_e32 v12, 16, v12
	v_and_b32_e32 v14, 0xffff0000, v168
	v_lshlrev_b32_e32 v15, 16, v168
	v_and_or_b32 v12, v13, s14, v12
	v_pk_fma_f32 v[8:9], v[4:5], v[8:9], v[14:15]
	global_store_dword v[6:7], v12, off
	v_lshl_add_u64 v[6:7], v[6:7], 0, s[38:39]
	s_waitcnt vmcnt(31)
	v_bfe_u32 v12, v9, 16, 1
	v_bfe_u32 v13, v8, 16, 1
	v_add3_u32 v12, v9, v12, s65
	v_add3_u32 v13, v8, v13, s65
	v_lshrrev_b32_e32 v12, 16, v12
	v_and_b32_e32 v14, 0xffff0000, v169
	v_lshlrev_b32_e32 v15, 16, v169
	v_and_or_b32 v12, v13, s14, v12
	v_pk_fma_f32 v[8:9], v[4:5], v[8:9], v[14:15]
	global_store_dword v[6:7], v12, off
	v_lshl_add_u64 v[6:7], v[6:7], 0, s[38:39]
	s_waitcnt vmcnt(31)
	v_bfe_u32 v12, v9, 16, 1
	v_bfe_u32 v13, v8, 16, 1
	v_add3_u32 v12, v9, v12, s65
	v_add3_u32 v13, v8, v13, s65
	v_lshrrev_b32_e32 v12, 16, v12
	v_and_b32_e32 v14, 0xffff0000, v170
	v_lshlrev_b32_e32 v15, 16, v170
	v_and_or_b32 v12, v13, s14, v12
	v_pk_fma_f32 v[8:9], v[4:5], v[8:9], v[14:15]
	global_store_dword v[6:7], v12, off
	v_lshl_add_u64 v[6:7], v[6:7], 0, s[38:39]
	s_waitcnt vmcnt(31)
	v_bfe_u32 v12, v9, 16, 1
	v_bfe_u32 v13, v8, 16, 1
	v_add3_u32 v12, v9, v12, s65
	v_add3_u32 v13, v8, v13, s65
	v_lshrrev_b32_e32 v12, 16, v12
	v_and_b32_e32 v14, 0xffff0000, v171
	v_lshlrev_b32_e32 v15, 16, v171
	v_and_or_b32 v12, v13, s14, v12
	v_pk_fma_f32 v[8:9], v[4:5], v[8:9], v[14:15]
	global_store_dword v[6:7], v12, off
	v_lshl_add_u64 v[6:7], v[6:7], 0, s[38:39]
	s_waitcnt vmcnt(31)
	v_bfe_u32 v12, v9, 16, 1
	v_bfe_u32 v13, v8, 16, 1
	v_add3_u32 v12, v9, v12, s65
	v_add3_u32 v13, v8, v13, s65
	v_lshrrev_b32_e32 v12, 16, v12
	v_and_b32_e32 v14, 0xffff0000, v172
	v_lshlrev_b32_e32 v15, 16, v172
	v_and_or_b32 v12, v13, s14, v12
	v_pk_fma_f32 v[8:9], v[4:5], v[8:9], v[14:15]
	global_store_dword v[6:7], v12, off
	v_lshl_add_u64 v[6:7], v[6:7], 0, s[38:39]
	s_waitcnt vmcnt(31)
	v_bfe_u32 v12, v9, 16, 1
	v_bfe_u32 v13, v8, 16, 1
	v_add3_u32 v12, v9, v12, s65
	v_add3_u32 v13, v8, v13, s65
	v_lshrrev_b32_e32 v12, 16, v12
	v_and_b32_e32 v14, 0xffff0000, v173
	v_lshlrev_b32_e32 v15, 16, v173
	v_and_or_b32 v12, v13, s14, v12
	v_pk_fma_f32 v[8:9], v[4:5], v[8:9], v[14:15]
	global_store_dword v[6:7], v12, off
	v_lshl_add_u64 v[6:7], v[6:7], 0, s[38:39]
	s_waitcnt vmcnt(31)
	v_bfe_u32 v12, v9, 16, 1
	v_bfe_u32 v13, v8, 16, 1
	v_add3_u32 v12, v9, v12, s65
	v_add3_u32 v13, v8, v13, s65
	v_lshrrev_b32_e32 v12, 16, v12
	v_and_b32_e32 v14, 0xffff0000, v174
	v_lshlrev_b32_e32 v15, 16, v174
	v_and_or_b32 v12, v13, s14, v12
	v_pk_fma_f32 v[8:9], v[4:5], v[8:9], v[14:15]
	global_store_dword v[6:7], v12, off
	v_lshl_add_u64 v[6:7], v[6:7], 0, s[38:39]
	s_waitcnt vmcnt(31)
	v_bfe_u32 v12, v9, 16, 1
	v_bfe_u32 v13, v8, 16, 1
	v_add3_u32 v12, v9, v12, s65
	v_add3_u32 v13, v8, v13, s65
	v_lshrrev_b32_e32 v12, 16, v12
	v_and_b32_e32 v14, 0xffff0000, v175
	v_lshlrev_b32_e32 v15, 16, v175
	v_and_or_b32 v12, v13, s14, v12
	v_pk_fma_f32 v[8:9], v[4:5], v[8:9], v[14:15]
	global_store_dword v[6:7], v12, off
	v_lshl_add_u64 v[6:7], v[6:7], 0, s[38:39]
	s_cmpk_gt_u32 s11, 0x5f
	s_cbranch_scc0 .LBB0_954
	v_readlane_b32 s4, v251, 32
	v_readlane_b32 s5, v251, 33
	s_mov_b64 s[38:39], 0xffff
	s_nop 0
	v_lshl_add_u64 v[0:1], v[0:1], 0, s[4:5]
	v_readlane_b32 s4, v251, 52
	v_cmp_lt_i64_e32 vcc, s[38:39], v[0:1]
	v_readlane_b32 s5, v251, 53
	s_or_b64 s[2:3], vcc, s[2:3]
	s_nop 0
	v_lshl_add_u64 v[2:3], v[2:3], 0, s[4:5]
	s_andn2_b64 exec, exec, s[2:3]
	s_cbranch_execnz .LBB0_953
